# layout 4 + nt (streaming) hint on the deferred routines' bf16 stores
# speedup vs baseline: 1.0017x; 1.0017x over previous
.Ldm8_job:
	s_add_u32 s91, s91, s2
	s_cmp_ge_u32 s91, s93
	s_cbranch_scc1 .Ldm8_disp
	s_load_dwordx2 s[6:7], s[86:87], 0x98
	s_load_dwordx2 s[88:89], s[86:87], 0xb0
	s_mul_i32 s48, s69, 0x4000000
	s_waitcnt lgkmcnt(0)
	s_add_u32 s6, s6, s48
	s_addc_u32 s7, s7, 0
	s_mul_i32 s48, s69, 0x2000000
	s_add_u32 s88, s88, 0x76b32000
	s_addc_u32 s89, s89, 0
	s_add_u32 s88, s88, s48
	s_addc_u32 s89, s89, 0
	s_lshr_b32 s72, s91, 6
	s_and_b32 s73, s91, 63
	s_lshl_b32 s56, s72, 19
	s_lshl_b32 s57, s73, 7
	s_add_u32 s56, s56, s57
	s_add_u32 s50, s6, s56
	s_addc_u32 s51, s7, 0
	global_load_dwordx4 v[58:61], v44, s[50:51] nt
	global_load_dwordx4 v[62:65], v45, s[50:51] nt
	global_load_dwordx4 v[66:69], v46, s[50:51] nt
	global_load_dwordx4 v[70:73], v47, s[50:51] nt
	global_load_dwordx4 v[74:77], v48, s[50:51] nt
	global_load_dwordx4 v[78:81], v49, s[50:51] nt
	global_load_dwordx4 v[82:85], v50, s[50:51] nt
	global_load_dwordx4 v[86:89], v51, s[50:51] nt
	s_add_u32 s71, s91, s92
	s_cmp_ge_u32 s71, s93
	s_cbranch_scc1 .Ldm8_first0
	s_lshr_b32 s72, s71, 6
	s_and_b32 s73, s71, 63
	s_lshl_b32 s56, s72, 19
	s_lshl_b32 s57, s73, 7
	s_add_u32 s56, s56, s57
	s_add_u32 s50, s6, s56
	s_addc_u32 s51, s7, 0
	global_load_dwordx4 v[90:93], v44, s[50:51] nt
	global_load_dwordx4 v[94:97], v45, s[50:51] nt
	global_load_dwordx4 v[98:101], v46, s[50:51] nt
	global_load_dwordx4 v[102:105], v47, s[50:51] nt
	global_load_dwordx4 v[106:109], v48, s[50:51] nt
	global_load_dwordx4 v[110:113], v49, s[50:51] nt
	global_load_dwordx4 v[114:117], v50, s[50:51] nt
	global_load_dwordx4 v[118:121], v51, s[50:51] nt
	s_waitcnt vmcnt(8)
	s_branch .Ldm8_loop

.Ldm8_nopfa:
	ds_read2_b32 v[122:123], v53 offset0:0 offset1:33
	ds_read2_b32 v[124:125], v53 offset0:66 offset1:99
	ds_read2_b32 v[126:127], v53 offset0:132 offset1:165
	ds_read2_b32 v[128:129], v53 offset0:198 offset1:231
	ds_read2_b32 v[130:131], v53 offset0:8 offset1:41
	ds_read2_b32 v[132:133], v53 offset0:74 offset1:107
	ds_read2_b32 v[134:135], v53 offset0:140 offset1:173
	ds_read2_b32 v[136:137], v53 offset0:206 offset1:239
	ds_read2_b32 v[138:139], v53 offset0:16 offset1:49
	ds_read2_b32 v[140:141], v53 offset0:82 offset1:115
	ds_read2_b32 v[142:143], v53 offset0:148 offset1:181
	ds_read2_b32 v[144:145], v53 offset0:214 offset1:247
	ds_read2_b32 v[146:147], v53 offset0:24 offset1:57
	ds_read2_b32 v[148:149], v53 offset0:90 offset1:123
	ds_read2_b32 v[180:181], v53 offset0:156 offset1:189
	ds_read2_b32 v[182:183], v53 offset0:222 offset1:255
	s_waitcnt lgkmcnt(0)
	v_cvt_pk_bf16_f32 v184, v122, v123
	v_cvt_pk_bf16_f32 v185, v124, v125
	v_cvt_pk_bf16_f32 v186, v126, v127
	v_cvt_pk_bf16_f32 v187, v128, v129
	v_cvt_pk_bf16_f32 v188, v130, v131
	v_cvt_pk_bf16_f32 v189, v132, v133
	v_cvt_pk_bf16_f32 v190, v134, v135
	v_cvt_pk_bf16_f32 v191, v136, v137
	v_cvt_pk_bf16_f32 v192, v138, v139
	v_cvt_pk_bf16_f32 v193, v140, v141
	v_cvt_pk_bf16_f32 v194, v142, v143
	v_cvt_pk_bf16_f32 v195, v144, v145
	v_cvt_pk_bf16_f32 v196, v146, v147
	v_cvt_pk_bf16_f32 v197, v148, v149
	v_cvt_pk_bf16_f32 v198, v180, v181
	v_cvt_pk_bf16_f32 v199, v182, v183
	v_add_u32_e32 v200, s58, v54
	v_add_u32_e32 v201, s58, v55
	v_add_u32_e32 v202, s58, v56
	v_add_u32_e32 v203, s58, v57
	global_store_dwordx4 v200, v[184:187], s[88:89] nt
	global_store_dwordx4 v201, v[188:191], s[88:89] nt
	global_store_dwordx4 v202, v[192:195], s[88:89] nt
	global_store_dwordx4 v203, v[196:199], s[88:89] nt
	s_cmp_ge_u32 s71, s93
	s_cbranch_scc1 .Ldm8_jobend
	s_cmp_ge_u32 s91, s93
	s_cbranch_scc1 .Ldm8_w4a
	s_waitcnt vmcnt(12)
	s_branch .Ldm8_goa

.Ldm8_nopfb:
	ds_read2_b32 v[122:123], v53 offset0:0 offset1:33
	ds_read2_b32 v[124:125], v53 offset0:66 offset1:99
	ds_read2_b32 v[126:127], v53 offset0:132 offset1:165
	ds_read2_b32 v[128:129], v53 offset0:198 offset1:231
	ds_read2_b32 v[130:131], v53 offset0:8 offset1:41
	ds_read2_b32 v[132:133], v53 offset0:74 offset1:107
	ds_read2_b32 v[134:135], v53 offset0:140 offset1:173
	ds_read2_b32 v[136:137], v53 offset0:206 offset1:239
	ds_read2_b32 v[138:139], v53 offset0:16 offset1:49
	ds_read2_b32 v[140:141], v53 offset0:82 offset1:115
	ds_read2_b32 v[142:143], v53 offset0:148 offset1:181
	ds_read2_b32 v[144:145], v53 offset0:214 offset1:247
	ds_read2_b32 v[146:147], v53 offset0:24 offset1:57
	ds_read2_b32 v[148:149], v53 offset0:90 offset1:123
	ds_read2_b32 v[180:181], v53 offset0:156 offset1:189
	ds_read2_b32 v[182:183], v53 offset0:222 offset1:255
	s_waitcnt lgkmcnt(0)
	v_cvt_pk_bf16_f32 v184, v122, v123
	v_cvt_pk_bf16_f32 v185, v124, v125
	v_cvt_pk_bf16_f32 v186, v126, v127
	v_cvt_pk_bf16_f32 v187, v128, v129
	v_cvt_pk_bf16_f32 v188, v130, v131
	v_cvt_pk_bf16_f32 v189, v132, v133
	v_cvt_pk_bf16_f32 v190, v134, v135
	v_cvt_pk_bf16_f32 v191, v136, v137
	v_cvt_pk_bf16_f32 v192, v138, v139
	v_cvt_pk_bf16_f32 v193, v140, v141
	v_cvt_pk_bf16_f32 v194, v142, v143
	v_cvt_pk_bf16_f32 v195, v144, v145
	v_cvt_pk_bf16_f32 v196, v146, v147
	v_cvt_pk_bf16_f32 v197, v148, v149
	v_cvt_pk_bf16_f32 v198, v180, v181
	v_cvt_pk_bf16_f32 v199, v182, v183
	v_add_u32_e32 v200, s58, v54
	v_add_u32_e32 v201, s58, v55
	v_add_u32_e32 v202, s58, v56
	v_add_u32_e32 v203, s58, v57
	global_store_dwordx4 v200, v[184:187], s[88:89] nt
	global_store_dwordx4 v201, v[188:191], s[88:89] nt
	global_store_dwordx4 v202, v[192:195], s[88:89] nt
	global_store_dwordx4 v203, v[196:199], s[88:89] nt
	s_cmp_ge_u32 s91, s93
	s_cbranch_scc1 .Ldm8_jobend
	s_cmp_ge_u32 s71, s93
	s_cbranch_scc1 .Ldm8_w4b
	s_waitcnt vmcnt(12)
	s_branch .Ldm8_gob

.Ldm7_job:
	s_add_u32 s91, s91, s2
	s_cmp_ge_u32 s91, s93
	s_cbranch_scc1 .Ldm7_disp
	s_load_dwordx2 s[6:7], s[86:87], 0x90
	s_load_dwordx2 s[88:89], s[86:87], 0xb0
	s_load_dwordx2 s[74:75], s[86:87], 0x88
	s_mul_i32 s48, s69, 0x4000000
	s_waitcnt lgkmcnt(0)
	s_add_u32 s6, s6, s48
	s_addc_u32 s7, s7, 0
	s_mul_i32 s48, s69, 0x2000000
	s_add_u32 s88, s88, 0x6eb32000
	s_addc_u32 s89, s89, 0
	s_add_u32 s88, s88, s48
	s_addc_u32 s89, s89, 0
	s_lshl_b32 s48, s69, 13
	s_add_u32 s74, s74, s48
	s_addc_u32 s75, s75, 0
	s_lshr_b32 s72, s91, 8
	s_and_b32 s73, s91, 255
	s_lshl_b32 s56, s72, 21
	s_lshl_b32 s57, s73, 7
	s_add_u32 s56, s56, s57
	s_add_u32 s50, s6, s56
	s_addc_u32 s51, s7, 0
	global_load_dwordx4 v[58:61], v44, s[50:51] nt
	global_load_dwordx4 v[62:65], v45, s[50:51] nt
	global_load_dwordx4 v[66:69], v46, s[50:51] nt
	global_load_dwordx4 v[70:73], v47, s[50:51] nt
	global_load_dwordx4 v[74:77], v48, s[50:51] nt
	global_load_dwordx4 v[78:81], v49, s[50:51] nt
	global_load_dwordx4 v[82:85], v50, s[50:51] nt
	global_load_dwordx4 v[86:89], v51, s[50:51] nt
	s_lshl_b32 s56, s72, 8
	s_add_u32 s50, s74, s56
	s_addc_u32 s51, s75, 0
	global_load_dword v230, v204, s[50:51] offset:0
	global_load_dword v231, v204, s[50:51] offset:32
	global_load_dword v232, v204, s[50:51] offset:64
	global_load_dword v233, v204, s[50:51] offset:96
	global_load_dword v234, v204, s[50:51] offset:128
	global_load_dword v235, v204, s[50:51] offset:160
	global_load_dword v236, v204, s[50:51] offset:192
	global_load_dword v237, v204, s[50:51] offset:224
	s_add_u32 s71, s91, s92
	s_cmp_ge_u32 s71, s93
	s_cbranch_scc1 .Ldm7_first0
	s_lshr_b32 s72, s71, 8
	s_and_b32 s73, s71, 255
	s_lshl_b32 s56, s72, 21
	s_lshl_b32 s57, s73, 7
	s_add_u32 s56, s56, s57
	s_add_u32 s50, s6, s56
	s_addc_u32 s51, s7, 0
	global_load_dwordx4 v[90:93], v44, s[50:51] nt
	global_load_dwordx4 v[94:97], v45, s[50:51] nt
	global_load_dwordx4 v[98:101], v46, s[50:51] nt
	global_load_dwordx4 v[102:105], v47, s[50:51] nt
	global_load_dwordx4 v[106:109], v48, s[50:51] nt
	global_load_dwordx4 v[110:113], v49, s[50:51] nt
	global_load_dwordx4 v[114:117], v50, s[50:51] nt
	global_load_dwordx4 v[118:121], v51, s[50:51] nt
	s_lshl_b32 s56, s72, 8
	s_add_u32 s50, s74, s56
	s_addc_u32 s51, s75, 0
	global_load_dword v238, v204, s[50:51] offset:0
	global_load_dword v239, v204, s[50:51] offset:32
	global_load_dword v240, v204, s[50:51] offset:64
	global_load_dword v241, v204, s[50:51] offset:96
	global_load_dword v242, v204, s[50:51] offset:128
	global_load_dword v243, v204, s[50:51] offset:160
	global_load_dword v244, v204, s[50:51] offset:192
	global_load_dword v245, v204, s[50:51] offset:224
	s_waitcnt vmcnt(16)
	s_branch .Ldm7_loop

.Ldm7_nopfa:
	ds_read2_b32 v[122:123], v53 offset0:0 offset1:33
	ds_read2_b32 v[124:125], v53 offset0:66 offset1:99
	ds_read2_b32 v[126:127], v53 offset0:132 offset1:165
	ds_read2_b32 v[128:129], v53 offset0:198 offset1:231
	ds_read2_b32 v[130:131], v53 offset0:8 offset1:41
	ds_read2_b32 v[132:133], v53 offset0:74 offset1:107
	ds_read2_b32 v[134:135], v53 offset0:140 offset1:173
	ds_read2_b32 v[136:137], v53 offset0:206 offset1:239
	ds_read2_b32 v[138:139], v53 offset0:16 offset1:49
	ds_read2_b32 v[140:141], v53 offset0:82 offset1:115
	ds_read2_b32 v[142:143], v53 offset0:148 offset1:181
	ds_read2_b32 v[144:145], v53 offset0:214 offset1:247
	ds_read2_b32 v[146:147], v53 offset0:24 offset1:57
	ds_read2_b32 v[148:149], v53 offset0:90 offset1:123
	ds_read2_b32 v[180:181], v53 offset0:156 offset1:189
	ds_read2_b32 v[182:183], v53 offset0:222 offset1:255
	s_waitcnt lgkmcnt(0)
	v_cvt_pk_bf16_f32 v184, v122, v123
	v_cvt_pk_bf16_f32 v185, v124, v125
	v_cvt_pk_bf16_f32 v186, v126, v127
	v_cvt_pk_bf16_f32 v187, v128, v129
	v_cvt_pk_bf16_f32 v188, v130, v131
	v_cvt_pk_bf16_f32 v189, v132, v133
	v_cvt_pk_bf16_f32 v190, v134, v135
	v_cvt_pk_bf16_f32 v191, v136, v137
	v_cvt_pk_bf16_f32 v192, v138, v139
	v_cvt_pk_bf16_f32 v193, v140, v141
	v_cvt_pk_bf16_f32 v194, v142, v143
	v_cvt_pk_bf16_f32 v195, v144, v145
	v_cvt_pk_bf16_f32 v196, v146, v147
	v_cvt_pk_bf16_f32 v197, v148, v149
	v_cvt_pk_bf16_f32 v198, v180, v181
	v_cvt_pk_bf16_f32 v199, v182, v183
	v_add_u32_e32 v200, s58, v54
	v_add_u32_e32 v201, s58, v55
	v_add_u32_e32 v202, s58, v56
	v_add_u32_e32 v203, s58, v57
	global_store_dwordx4 v200, v[184:187], s[88:89] nt
	global_store_dwordx4 v201, v[188:191], s[88:89] nt
	global_store_dwordx4 v202, v[192:195], s[88:89] nt
	global_store_dwordx4 v203, v[196:199], s[88:89] nt
	s_cmp_ge_u32 s71, s93
	s_cbranch_scc1 .Ldm7_jobend
	s_cmp_ge_u32 s91, s93
	s_cbranch_scc1 .Ldm7_w4a
	s_waitcnt vmcnt(20)
	s_branch .Ldm7_goa

.Ldm7_nopfb:
	ds_read2_b32 v[122:123], v53 offset0:0 offset1:33
	ds_read2_b32 v[124:125], v53 offset0:66 offset1:99
	ds_read2_b32 v[126:127], v53 offset0:132 offset1:165
	ds_read2_b32 v[128:129], v53 offset0:198 offset1:231
	ds_read2_b32 v[130:131], v53 offset0:8 offset1:41
	ds_read2_b32 v[132:133], v53 offset0:74 offset1:107
	ds_read2_b32 v[134:135], v53 offset0:140 offset1:173
	ds_read2_b32 v[136:137], v53 offset0:206 offset1:239
	ds_read2_b32 v[138:139], v53 offset0:16 offset1:49
	ds_read2_b32 v[140:141], v53 offset0:82 offset1:115
	ds_read2_b32 v[142:143], v53 offset0:148 offset1:181
	ds_read2_b32 v[144:145], v53 offset0:214 offset1:247
	ds_read2_b32 v[146:147], v53 offset0:24 offset1:57
	ds_read2_b32 v[148:149], v53 offset0:90 offset1:123
	ds_read2_b32 v[180:181], v53 offset0:156 offset1:189
	ds_read2_b32 v[182:183], v53 offset0:222 offset1:255
	s_waitcnt lgkmcnt(0)
	v_cvt_pk_bf16_f32 v184, v122, v123
	v_cvt_pk_bf16_f32 v185, v124, v125
	v_cvt_pk_bf16_f32 v186, v126, v127
	v_cvt_pk_bf16_f32 v187, v128, v129
	v_cvt_pk_bf16_f32 v188, v130, v131
	v_cvt_pk_bf16_f32 v189, v132, v133
	v_cvt_pk_bf16_f32 v190, v134, v135
	v_cvt_pk_bf16_f32 v191, v136, v137
	v_cvt_pk_bf16_f32 v192, v138, v139
	v_cvt_pk_bf16_f32 v193, v140, v141
	v_cvt_pk_bf16_f32 v194, v142, v143
	v_cvt_pk_bf16_f32 v195, v144, v145
	v_cvt_pk_bf16_f32 v196, v146, v147
	v_cvt_pk_bf16_f32 v197, v148, v149
	v_cvt_pk_bf16_f32 v198, v180, v181
	v_cvt_pk_bf16_f32 v199, v182, v183
	v_add_u32_e32 v200, s58, v54
	v_add_u32_e32 v201, s58, v55
	v_add_u32_e32 v202, s58, v56
	v_add_u32_e32 v203, s58, v57
	global_store_dwordx4 v200, v[184:187], s[88:89] nt
	global_store_dwordx4 v201, v[188:191], s[88:89] nt
	global_store_dwordx4 v202, v[192:195], s[88:89] nt
	global_store_dwordx4 v203, v[196:199], s[88:89] nt
	s_cmp_ge_u32 s91, s93
	s_cbranch_scc1 .Ldm7_jobend
	s_cmp_ge_u32 s71, s93
	s_cbranch_scc1 .Ldm7_w4b
	s_waitcnt vmcnt(20)
	s_branch .Ldm7_gob

.Ldmc_ldend:
	s_waitcnt vmcnt(0)
	s_mov_b32 s71, s91
	s_cmp_ge_u32 s71, s79
	s_cbranch_scc1 .Ldmc_stend
	s_lshr_b32 s72, s71, 12
	s_and_b32 s73, s71, 0xfff
	s_mulk_i32 s72, 0x1100
	s_add_u32 s72, s72, s73
	s_mul_i32 s72, s72, 0x500
	s_add_u32 s50, s88, s72
	s_addc_u32 s51, s89, 0
	v_cvt_pk_bf16_f32 v122, v58, v59
	v_cvt_pk_bf16_f32 v123, v60, v61
	v_cvt_pk_bf16_f32 v124, v62, v63
	v_cvt_pk_bf16_f32 v125, v64, v65
	global_store_dwordx4 v43, v[122:125], s[50:51] nt
	s_add_u32 s71, s71, s92
	s_cmp_ge_u32 s71, s79
	s_cbranch_scc1 .Ldmc_stend
	s_lshr_b32 s72, s71, 12
	s_and_b32 s73, s71, 0xfff
	s_mulk_i32 s72, 0x1100
	s_add_u32 s72, s72, s73
	s_mul_i32 s72, s72, 0x500
	s_add_u32 s50, s88, s72
	s_addc_u32 s51, s89, 0
	v_cvt_pk_bf16_f32 v126, v66, v67
	v_cvt_pk_bf16_f32 v127, v68, v69
	v_cvt_pk_bf16_f32 v128, v70, v71
	v_cvt_pk_bf16_f32 v129, v72, v73
	global_store_dwordx4 v43, v[126:129], s[50:51] nt
	s_add_u32 s71, s71, s92
	s_cmp_ge_u32 s71, s79
	s_cbranch_scc1 .Ldmc_stend
	s_lshr_b32 s72, s71, 12
	s_and_b32 s73, s71, 0xfff
	s_mulk_i32 s72, 0x1100
	s_add_u32 s72, s72, s73
	s_mul_i32 s72, s72, 0x500
	s_add_u32 s50, s88, s72
	s_addc_u32 s51, s89, 0
	v_cvt_pk_bf16_f32 v130, v74, v75
	v_cvt_pk_bf16_f32 v131, v76, v77
	v_cvt_pk_bf16_f32 v132, v78, v79
	v_cvt_pk_bf16_f32 v133, v80, v81
	global_store_dwordx4 v43, v[130:133], s[50:51] nt
	s_add_u32 s71, s71, s92
	s_cmp_ge_u32 s71, s79
	s_cbranch_scc1 .Ldmc_stend
	s_lshr_b32 s72, s71, 12
	s_and_b32 s73, s71, 0xfff
	s_mulk_i32 s72, 0x1100
	s_add_u32 s72, s72, s73
	s_mul_i32 s72, s72, 0x500
	s_add_u32 s50, s88, s72
	s_addc_u32 s51, s89, 0
	v_cvt_pk_bf16_f32 v134, v82, v83
	v_cvt_pk_bf16_f32 v135, v84, v85
	v_cvt_pk_bf16_f32 v136, v86, v87
	v_cvt_pk_bf16_f32 v137, v88, v89
	global_store_dwordx4 v43, v[134:137], s[50:51] nt
	s_add_u32 s71, s71, s92
	s_cmp_ge_u32 s71, s79
	s_cbranch_scc1 .Ldmc_stend
	s_lshr_b32 s72, s71, 12
	s_and_b32 s73, s71, 0xfff
	s_mulk_i32 s72, 0x1100
	s_add_u32 s72, s72, s73
	s_mul_i32 s72, s72, 0x500
	s_add_u32 s50, s88, s72
	s_addc_u32 s51, s89, 0
	v_cvt_pk_bf16_f32 v138, v90, v91
	v_cvt_pk_bf16_f32 v139, v92, v93
	v_cvt_pk_bf16_f32 v140, v94, v95
	v_cvt_pk_bf16_f32 v141, v96, v97
	global_store_dwordx4 v43, v[138:141], s[50:51] nt
	s_add_u32 s71, s71, s92
	s_cmp_ge_u32 s71, s79
	s_cbranch_scc1 .Ldmc_stend
	s_lshr_b32 s72, s71, 12
	s_and_b32 s73, s71, 0xfff
	s_mulk_i32 s72, 0x1100
	s_add_u32 s72, s72, s73
	s_mul_i32 s72, s72, 0x500
	s_add_u32 s50, s88, s72
	s_addc_u32 s51, s89, 0
	v_cvt_pk_bf16_f32 v142, v98, v99
	v_cvt_pk_bf16_f32 v143, v100, v101
	v_cvt_pk_bf16_f32 v144, v102, v103
	v_cvt_pk_bf16_f32 v145, v104, v105
	global_store_dwordx4 v43, v[142:145], s[50:51] nt
	s_add_u32 s71, s71, s92
	s_cmp_ge_u32 s71, s79
	s_cbranch_scc1 .Ldmc_stend
	s_lshr_b32 s72, s71, 12
	s_and_b32 s73, s71, 0xfff
	s_mulk_i32 s72, 0x1100
	s_add_u32 s72, s72, s73
	s_mul_i32 s72, s72, 0x500
	s_add_u32 s50, s88, s72
	s_addc_u32 s51, s89, 0
	v_cvt_pk_bf16_f32 v146, v106, v107
	v_cvt_pk_bf16_f32 v147, v108, v109
	v_cvt_pk_bf16_f32 v148, v110, v111
	v_cvt_pk_bf16_f32 v149, v112, v113
	global_store_dwordx4 v43, v[146:149], s[50:51] nt
	s_add_u32 s71, s71, s92
	s_cmp_ge_u32 s71, s79
	s_cbranch_scc1 .Ldmc_stend
	s_lshr_b32 s72, s71, 12
	s_and_b32 s73, s71, 0xfff
	s_mulk_i32 s72, 0x1100
	s_add_u32 s72, s72, s73
	s_mul_i32 s72, s72, 0x500
	s_add_u32 s50, s88, s72
	s_addc_u32 s51, s89, 0
	v_cvt_pk_bf16_f32 v180, v114, v115
	v_cvt_pk_bf16_f32 v181, v116, v117
	v_cvt_pk_bf16_f32 v182, v118, v119
	v_cvt_pk_bf16_f32 v183, v120, v121
	global_store_dwordx4 v43, v[180:183], s[50:51] nt
	s_add_u32 s71, s71, s92
